# merge epilogue: final (z=3) merged stores write-through sc1 so they do not occupy L2
# speedup vs baseline: 1.0105x; 1.0081x over previous
.LBB0_1020:
	s_lshl_b32 s13, s20, 8
	s_lshl_b32 s20, s5, 10
	v_mbcnt_lo_u32_b32 v16, -1, 0
	v_mbcnt_hi_u32_b32 v16, -1, v16
	s_lshl_b32 s4, s4, 8
	v_and_or_b32 v176, v16, 15, s45
	s_ashr_i32 s21, s20, 31
	v_ashrrev_i32_e32 v16, 1, v16
	v_add_u32_e32 v168, s13, v176
	s_or_b32 s4, s4, s46
	s_lshl_b64 s[20:21], s[20:21], 1
	v_and_b32_e32 v16, -8, v16
	s_add_u32 s20, s43, s20
	v_ashrrev_i32_e32 v169, 31, v168
	v_add_u32_e32 v166, s4, v16
	s_addc_u32 s21, s44, s21
	v_lshlrev_b64 v[16:17], 13, v[168:169]
	v_lshl_add_u64 v[16:17], s[20:21], 0, v[16:17]
	v_ashrrev_i32_e32 v167, 31, v166
	v_lshl_add_u64 v[16:17], v[166:167], 1, v[16:17]
	v_lshlrev_b64 v[18:19], 11, v[168:169]
	v_lshl_add_u64 v[18:19], s[8:9], 0, v[18:19]
	v_lshl_add_u64 v[172:173], v[166:167], 1, v[18:19]
	v_mov_b64_e32 v[170:171], v[16:17]
	v_mov_b64_e32 v[230:231], v[250:251]
	v_mov_b32_e32 v243, v249
	v_mov_b32_e32 v251, v248
	v_mov_b32_e32 v249, 0x358637bd
	v_mov_b32_e32 v248, 0x260
	s_mov_b32 s59, 0
	s_waitcnt lgkmcnt(0)
	s_cmp_eq_u32 s5, 0
	s_cbranch_scc1 .Lmepi_z0
	s_cmp_eq_u32 s5, 3
	s_cbranch_scc1 .Lmepi_z3
	global_load_dwordx4 v[180:183], v[170:171], off nt
	global_load_dwordx4 v[184:187], v[170:171], off offset:256 nt
	global_load_dwordx4 v[188:191], v[172:173], off
	global_load_dwordx4 v[192:195], v[172:173], off offset:256
	s_mov_b32 s58, 0x20000
	v_lshl_add_u64 v[244:245], v[170:171], 0, s[58:59]
	global_load_dwordx4 v[196:199], v[244:245], off nt
	global_load_dwordx4 v[200:203], v[244:245], off offset:256 nt
	s_mov_b32 s58, 0x8000
	v_lshl_add_u64 v[246:247], v[172:173], 0, s[58:59]
	global_load_dwordx4 v[204:207], v[246:247], off
	global_load_dwordx4 v[208:211], v[246:247], off offset:256
	s_mov_b32 s58, 0x40000
	v_lshl_add_u64 v[252:253], v[170:171], 0, s[58:59]
	global_load_dwordx4 v[222:225], v[252:253], off nt
	global_load_dwordx4 v[226:229], v[252:253], off offset:256 nt
	s_mov_b32 s58, 0x10000
	v_lshl_add_u64 v[178:179], v[172:173], 0, s[58:59]
	global_load_dwordx4 v[234:237], v[178:179], off
	global_load_dwordx4 v[238:241], v[178:179], off offset:256
	s_mov_b32 s58, 0x60000
	v_lshl_add_u64 v[244:245], v[170:171], 0, s[58:59]
	global_load_dwordx4 v[16:19], v[244:245], off nt
	global_load_dwordx4 v[24:27], v[244:245], off offset:256 nt
	s_mov_b32 s58, 0x18000
	v_lshl_add_u64 v[246:247], v[172:173], 0, s[58:59]
	global_load_dwordx4 v[32:35], v[246:247], off
	global_load_dwordx4 v[44:47], v[246:247], off offset:256
	s_mov_b32 s58, 0x100000
	v_lshl_add_u64 v[252:253], v[170:171], 0, s[58:59]
	global_load_dwordx4 v[136:139], v[252:253], off nt
	global_load_dwordx4 v[148:151], v[252:253], off offset:256 nt
	s_mov_b32 s58, 0x40000
	v_lshl_add_u64 v[178:179], v[172:173], 0, s[58:59]
	global_load_dwordx4 v[152:155], v[178:179], off
	global_load_dwordx4 v[156:159], v[178:179], off offset:256
	s_waitcnt vmcnt(17)
	v_lshlrev_b32_e32 v244, 16, v180
	v_and_b32_e32 v245, 0xffff0000, v180
	v_pk_mul_f32 v[144:145], v[144:145], v[244:245]
	v_lshlrev_b32_e32 v246, 16, v181
	v_and_b32_e32 v247, 0xffff0000, v181
	v_pk_mul_f32 v[146:147], v[146:147], v[246:247]
	v_lshlrev_b32_e32 v252, 16, v182
	v_and_b32_e32 v253, 0xffff0000, v182
	v_pk_mul_f32 v[140:141], v[140:141], v[252:253]
	v_lshlrev_b32_e32 v178, 16, v183
	v_and_b32_e32 v179, 0xffff0000, v183
	v_pk_mul_f32 v[142:143], v[142:143], v[178:179]
	v_lshlrev_b32_e32 v244, 16, v188
	v_and_b32_e32 v245, 0xffff0000, v188
	v_pk_add_f32 v[144:145], v[144:145], v[244:245]
	v_lshlrev_b32_e32 v246, 16, v189
	v_and_b32_e32 v247, 0xffff0000, v189
	v_pk_add_f32 v[146:147], v[146:147], v[246:247]
	v_lshlrev_b32_e32 v252, 16, v190
	v_and_b32_e32 v253, 0xffff0000, v190
	v_pk_add_f32 v[140:141], v[140:141], v[252:253]
	v_lshlrev_b32_e32 v178, 16, v191
	v_and_b32_e32 v179, 0xffff0000, v191
	v_pk_add_f32 v[142:143], v[142:143], v[178:179]
	v_cvt_pk_bf16_f32 v180, v144, v145
	v_cvt_pk_bf16_f32 v181, v146, v147
	v_cvt_pk_bf16_f32 v182, v140, v141
	v_cvt_pk_bf16_f32 v183, v142, v143
	global_store_dwordx4 v[172:173], v[180:183], off
	s_waitcnt vmcnt(17)
	v_lshlrev_b32_e32 v244, 16, v184
	v_and_b32_e32 v245, 0xffff0000, v184
	v_pk_mul_f32 v[132:133], v[132:133], v[244:245]
	v_lshlrev_b32_e32 v246, 16, v185
	v_and_b32_e32 v247, 0xffff0000, v185
	v_pk_mul_f32 v[134:135], v[134:135], v[246:247]
	v_lshlrev_b32_e32 v252, 16, v186
	v_and_b32_e32 v253, 0xffff0000, v186
	v_pk_mul_f32 v[128:129], v[128:129], v[252:253]
	v_lshlrev_b32_e32 v178, 16, v187
	v_and_b32_e32 v179, 0xffff0000, v187
	v_pk_mul_f32 v[130:131], v[130:131], v[178:179]
	v_lshlrev_b32_e32 v244, 16, v192
	v_and_b32_e32 v245, 0xffff0000, v192
	v_pk_add_f32 v[132:133], v[132:133], v[244:245]
	v_lshlrev_b32_e32 v246, 16, v193
	v_and_b32_e32 v247, 0xffff0000, v193
	v_pk_add_f32 v[134:135], v[134:135], v[246:247]
	v_lshlrev_b32_e32 v252, 16, v194
	v_and_b32_e32 v253, 0xffff0000, v194
	v_pk_add_f32 v[128:129], v[128:129], v[252:253]
	v_lshlrev_b32_e32 v178, 16, v195
	v_and_b32_e32 v179, 0xffff0000, v195
	v_pk_add_f32 v[130:131], v[130:131], v[178:179]
	v_cvt_pk_bf16_f32 v184, v132, v133
	v_cvt_pk_bf16_f32 v185, v134, v135
	v_cvt_pk_bf16_f32 v186, v128, v129
	v_cvt_pk_bf16_f32 v187, v130, v131
	global_store_dwordx4 v[172:173], v[184:187], off offset:256
	s_mov_b32 s58, 0x120000
	v_lshl_add_u64 v[244:245], v[170:171], 0, s[58:59]
	global_load_dwordx4 v[140:143], v[244:245], off nt
	global_load_dwordx4 v[144:147], v[244:245], off offset:256 nt
	s_mov_b32 s58, 0x48000
	v_lshl_add_u64 v[246:247], v[172:173], 0, s[58:59]
	global_load_dwordx4 v[180:183], v[246:247], off
	global_load_dwordx4 v[188:191], v[246:247], off offset:256
	s_mov_b32 s58, 0x140000
	v_lshl_add_u64 v[252:253], v[170:171], 0, s[58:59]
	global_load_dwordx4 v[128:131], v[252:253], off nt
	global_load_dwordx4 v[132:135], v[252:253], off offset:256 nt
	s_mov_b32 s58, 0x50000
	v_lshl_add_u64 v[178:179], v[172:173], 0, s[58:59]
	global_load_dwordx4 v[184:187], v[178:179], off
	global_load_dwordx4 v[192:195], v[178:179], off offset:256
	s_waitcnt vmcnt(23)
	v_lshlrev_b32_e32 v244, 16, v196
	v_and_b32_e32 v245, 0xffff0000, v196
	v_pk_mul_f32 v[124:125], v[124:125], v[244:245]
	v_lshlrev_b32_e32 v246, 16, v197
	v_and_b32_e32 v247, 0xffff0000, v197
	v_pk_mul_f32 v[126:127], v[126:127], v[246:247]
	v_lshlrev_b32_e32 v252, 16, v198
	v_and_b32_e32 v253, 0xffff0000, v198
	v_pk_mul_f32 v[120:121], v[120:121], v[252:253]
	v_lshlrev_b32_e32 v178, 16, v199
	v_and_b32_e32 v179, 0xffff0000, v199
	v_pk_mul_f32 v[122:123], v[122:123], v[178:179]
	v_lshlrev_b32_e32 v244, 16, v204
	v_and_b32_e32 v245, 0xffff0000, v204
	v_pk_add_f32 v[124:125], v[124:125], v[244:245]
	v_lshlrev_b32_e32 v246, 16, v205
	v_and_b32_e32 v247, 0xffff0000, v205
	v_pk_add_f32 v[126:127], v[126:127], v[246:247]
	v_lshlrev_b32_e32 v252, 16, v206
	v_and_b32_e32 v253, 0xffff0000, v206
	v_pk_add_f32 v[120:121], v[120:121], v[252:253]
	v_lshlrev_b32_e32 v178, 16, v207
	v_and_b32_e32 v179, 0xffff0000, v207
	v_pk_add_f32 v[122:123], v[122:123], v[178:179]
	v_cvt_pk_bf16_f32 v196, v124, v125
	v_cvt_pk_bf16_f32 v197, v126, v127
	v_cvt_pk_bf16_f32 v198, v120, v121
	v_cvt_pk_bf16_f32 v199, v122, v123
	s_mov_b32 s58, 0x8000
	v_lshl_add_u64 v[244:245], v[172:173], 0, s[58:59]
	global_store_dwordx4 v[244:245], v[196:199], off
	s_waitcnt vmcnt(23)
	v_lshlrev_b32_e32 v246, 16, v200
	v_and_b32_e32 v247, 0xffff0000, v200
	v_pk_mul_f32 v[116:117], v[116:117], v[246:247]
	v_lshlrev_b32_e32 v252, 16, v201
	v_and_b32_e32 v253, 0xffff0000, v201
	v_pk_mul_f32 v[118:119], v[118:119], v[252:253]
	v_lshlrev_b32_e32 v178, 16, v202
	v_and_b32_e32 v179, 0xffff0000, v202
	v_pk_mul_f32 v[112:113], v[112:113], v[178:179]
	v_lshlrev_b32_e32 v244, 16, v203
	v_and_b32_e32 v245, 0xffff0000, v203
	v_pk_mul_f32 v[114:115], v[114:115], v[244:245]
	v_lshlrev_b32_e32 v246, 16, v208
	v_and_b32_e32 v247, 0xffff0000, v208
	v_pk_add_f32 v[116:117], v[116:117], v[246:247]
	v_lshlrev_b32_e32 v252, 16, v209
	v_and_b32_e32 v253, 0xffff0000, v209
	v_pk_add_f32 v[118:119], v[118:119], v[252:253]
	v_lshlrev_b32_e32 v178, 16, v210
	v_and_b32_e32 v179, 0xffff0000, v210
	v_pk_add_f32 v[112:113], v[112:113], v[178:179]
	v_lshlrev_b32_e32 v244, 16, v211
	v_and_b32_e32 v245, 0xffff0000, v211
	v_pk_add_f32 v[114:115], v[114:115], v[244:245]
	v_cvt_pk_bf16_f32 v200, v116, v117
	v_cvt_pk_bf16_f32 v201, v118, v119
	v_cvt_pk_bf16_f32 v202, v112, v113
	v_cvt_pk_bf16_f32 v203, v114, v115
	s_mov_b32 s58, 0x8000
	v_lshl_add_u64 v[246:247], v[172:173], 0, s[58:59]
	global_store_dwordx4 v[246:247], v[200:203], off offset:256
	s_mov_b32 s58, 0x160000
	v_lshl_add_u64 v[252:253], v[170:171], 0, s[58:59]
	global_load_dwordx4 v[120:123], v[252:253], off nt
	global_load_dwordx4 v[124:127], v[252:253], off offset:256 nt
	s_mov_b32 s58, 0x58000
	v_lshl_add_u64 v[178:179], v[172:173], 0, s[58:59]
	global_load_dwordx4 v[196:199], v[178:179], off
	global_load_dwordx4 v[204:207], v[178:179], off offset:256
	s_waitcnt vmcnt(25)
	v_lshlrev_b32_e32 v244, 16, v222
	v_and_b32_e32 v245, 0xffff0000, v222
	v_pk_mul_f32 v[108:109], v[108:109], v[244:245]
	v_lshlrev_b32_e32 v246, 16, v223
	v_and_b32_e32 v247, 0xffff0000, v223
	v_pk_mul_f32 v[110:111], v[110:111], v[246:247]
	v_lshlrev_b32_e32 v252, 16, v224
	v_and_b32_e32 v253, 0xffff0000, v224
	v_pk_mul_f32 v[104:105], v[104:105], v[252:253]
	v_lshlrev_b32_e32 v178, 16, v225
	v_and_b32_e32 v179, 0xffff0000, v225
	v_pk_mul_f32 v[106:107], v[106:107], v[178:179]
	v_lshlrev_b32_e32 v244, 16, v234
	v_and_b32_e32 v245, 0xffff0000, v234
	v_pk_add_f32 v[108:109], v[108:109], v[244:245]
	v_lshlrev_b32_e32 v246, 16, v235
	v_and_b32_e32 v247, 0xffff0000, v235
	v_pk_add_f32 v[110:111], v[110:111], v[246:247]
	v_lshlrev_b32_e32 v252, 16, v236
	v_and_b32_e32 v253, 0xffff0000, v236
	v_pk_add_f32 v[104:105], v[104:105], v[252:253]
	v_lshlrev_b32_e32 v178, 16, v237
	v_and_b32_e32 v179, 0xffff0000, v237
	v_pk_add_f32 v[106:107], v[106:107], v[178:179]
	v_cvt_pk_bf16_f32 v222, v108, v109
	v_cvt_pk_bf16_f32 v223, v110, v111
	v_cvt_pk_bf16_f32 v224, v104, v105
	v_cvt_pk_bf16_f32 v225, v106, v107
	s_mov_b32 s58, 0x10000
	v_lshl_add_u64 v[244:245], v[172:173], 0, s[58:59]
	global_store_dwordx4 v[244:245], v[222:225], off
	s_waitcnt vmcnt(25)
	v_lshlrev_b32_e32 v246, 16, v226
	v_and_b32_e32 v247, 0xffff0000, v226
	v_pk_mul_f32 v[100:101], v[100:101], v[246:247]
	v_lshlrev_b32_e32 v252, 16, v227
	v_and_b32_e32 v253, 0xffff0000, v227
	v_pk_mul_f32 v[102:103], v[102:103], v[252:253]
	v_lshlrev_b32_e32 v178, 16, v228
	v_and_b32_e32 v179, 0xffff0000, v228
	v_pk_mul_f32 v[96:97], v[96:97], v[178:179]
	v_lshlrev_b32_e32 v244, 16, v229
	v_and_b32_e32 v245, 0xffff0000, v229
	v_pk_mul_f32 v[98:99], v[98:99], v[244:245]
	v_lshlrev_b32_e32 v246, 16, v238
	v_and_b32_e32 v247, 0xffff0000, v238
	v_pk_add_f32 v[100:101], v[100:101], v[246:247]
	v_lshlrev_b32_e32 v252, 16, v239
	v_and_b32_e32 v253, 0xffff0000, v239
	v_pk_add_f32 v[102:103], v[102:103], v[252:253]
	v_lshlrev_b32_e32 v178, 16, v240
	v_and_b32_e32 v179, 0xffff0000, v240
	v_pk_add_f32 v[96:97], v[96:97], v[178:179]
	v_lshlrev_b32_e32 v244, 16, v241
	v_and_b32_e32 v245, 0xffff0000, v241
	v_pk_add_f32 v[98:99], v[98:99], v[244:245]
	v_cvt_pk_bf16_f32 v226, v100, v101
	v_cvt_pk_bf16_f32 v227, v102, v103
	v_cvt_pk_bf16_f32 v228, v96, v97
	v_cvt_pk_bf16_f32 v229, v98, v99
	s_mov_b32 s58, 0x10000
	v_lshl_add_u64 v[246:247], v[172:173], 0, s[58:59]
	global_store_dwordx4 v[246:247], v[226:229], off offset:256
	s_waitcnt vmcnt(23)
	v_lshlrev_b32_e32 v252, 16, v16
	v_and_b32_e32 v253, 0xffff0000, v16
	v_pk_mul_f32 v[92:93], v[92:93], v[252:253]
	v_lshlrev_b32_e32 v178, 16, v17
	v_and_b32_e32 v179, 0xffff0000, v17
	v_pk_mul_f32 v[94:95], v[94:95], v[178:179]
	v_lshlrev_b32_e32 v244, 16, v18
	v_and_b32_e32 v245, 0xffff0000, v18
	v_pk_mul_f32 v[88:89], v[88:89], v[244:245]
	v_lshlrev_b32_e32 v246, 16, v19
	v_and_b32_e32 v247, 0xffff0000, v19
	v_pk_mul_f32 v[90:91], v[90:91], v[246:247]
	v_lshlrev_b32_e32 v252, 16, v32
	v_and_b32_e32 v253, 0xffff0000, v32
	v_pk_add_f32 v[92:93], v[92:93], v[252:253]
	v_lshlrev_b32_e32 v178, 16, v33
	v_and_b32_e32 v179, 0xffff0000, v33
	v_pk_add_f32 v[94:95], v[94:95], v[178:179]
	v_lshlrev_b32_e32 v244, 16, v34
	v_and_b32_e32 v245, 0xffff0000, v34
	v_pk_add_f32 v[88:89], v[88:89], v[244:245]
	v_lshlrev_b32_e32 v246, 16, v35
	v_and_b32_e32 v247, 0xffff0000, v35
	v_pk_add_f32 v[90:91], v[90:91], v[246:247]
	v_cvt_pk_bf16_f32 v16, v92, v93
	v_cvt_pk_bf16_f32 v17, v94, v95
	v_cvt_pk_bf16_f32 v18, v88, v89
	v_cvt_pk_bf16_f32 v19, v90, v91
	s_mov_b32 s58, 0x18000
	v_lshl_add_u64 v[252:253], v[172:173], 0, s[58:59]
	global_store_dwordx4 v[252:253], v[16:19], off
	s_waitcnt vmcnt(23)
	v_lshlrev_b32_e32 v178, 16, v24
	v_and_b32_e32 v179, 0xffff0000, v24
	v_pk_mul_f32 v[84:85], v[84:85], v[178:179]
	v_lshlrev_b32_e32 v244, 16, v25
	v_and_b32_e32 v245, 0xffff0000, v25
	v_pk_mul_f32 v[86:87], v[86:87], v[244:245]
	v_lshlrev_b32_e32 v246, 16, v26
	v_and_b32_e32 v247, 0xffff0000, v26
	v_pk_mul_f32 v[80:81], v[80:81], v[246:247]
	v_lshlrev_b32_e32 v252, 16, v27
	v_and_b32_e32 v253, 0xffff0000, v27
	v_pk_mul_f32 v[82:83], v[82:83], v[252:253]
	v_lshlrev_b32_e32 v178, 16, v44
	v_and_b32_e32 v179, 0xffff0000, v44
	v_pk_add_f32 v[84:85], v[84:85], v[178:179]
	v_lshlrev_b32_e32 v244, 16, v45
	v_and_b32_e32 v245, 0xffff0000, v45
	v_pk_add_f32 v[86:87], v[86:87], v[244:245]
	v_lshlrev_b32_e32 v246, 16, v46
	v_and_b32_e32 v247, 0xffff0000, v46
	v_pk_add_f32 v[80:81], v[80:81], v[246:247]
	v_lshlrev_b32_e32 v252, 16, v47
	v_and_b32_e32 v253, 0xffff0000, v47
	v_pk_add_f32 v[82:83], v[82:83], v[252:253]
	v_cvt_pk_bf16_f32 v24, v84, v85
	v_cvt_pk_bf16_f32 v25, v86, v87
	v_cvt_pk_bf16_f32 v26, v80, v81
	v_cvt_pk_bf16_f32 v27, v82, v83
	s_mov_b32 s58, 0x18000
	v_lshl_add_u64 v[178:179], v[172:173], 0, s[58:59]
	global_store_dwordx4 v[178:179], v[24:27], off offset:256
	s_waitcnt vmcnt(21)
	v_lshlrev_b32_e32 v244, 16, v136
	v_and_b32_e32 v245, 0xffff0000, v136
	v_pk_mul_f32 v[76:77], v[76:77], v[244:245]
	v_lshlrev_b32_e32 v246, 16, v137
	v_and_b32_e32 v247, 0xffff0000, v137
	v_pk_mul_f32 v[78:79], v[78:79], v[246:247]
	v_lshlrev_b32_e32 v252, 16, v138
	v_and_b32_e32 v253, 0xffff0000, v138
	v_pk_mul_f32 v[72:73], v[72:73], v[252:253]
	v_lshlrev_b32_e32 v178, 16, v139
	v_and_b32_e32 v179, 0xffff0000, v139
	v_pk_mul_f32 v[74:75], v[74:75], v[178:179]
	v_lshlrev_b32_e32 v244, 16, v152
	v_and_b32_e32 v245, 0xffff0000, v152
	v_pk_add_f32 v[76:77], v[76:77], v[244:245]
	v_lshlrev_b32_e32 v246, 16, v153
	v_and_b32_e32 v247, 0xffff0000, v153
	v_pk_add_f32 v[78:79], v[78:79], v[246:247]
	v_lshlrev_b32_e32 v252, 16, v154
	v_and_b32_e32 v253, 0xffff0000, v154
	v_pk_add_f32 v[72:73], v[72:73], v[252:253]
	v_lshlrev_b32_e32 v178, 16, v155
	v_and_b32_e32 v179, 0xffff0000, v155
	v_pk_add_f32 v[74:75], v[74:75], v[178:179]
	v_cvt_pk_bf16_f32 v136, v76, v77
	v_cvt_pk_bf16_f32 v137, v78, v79
	v_cvt_pk_bf16_f32 v138, v72, v73
	v_cvt_pk_bf16_f32 v139, v74, v75
	s_mov_b32 s58, 0x40000
	v_lshl_add_u64 v[244:245], v[172:173], 0, s[58:59]
	global_store_dwordx4 v[244:245], v[136:139], off
	s_waitcnt vmcnt(21)
	v_lshlrev_b32_e32 v246, 16, v148
	v_and_b32_e32 v247, 0xffff0000, v148
	v_pk_mul_f32 v[68:69], v[68:69], v[246:247]
	v_lshlrev_b32_e32 v252, 16, v149
	v_and_b32_e32 v253, 0xffff0000, v149
	v_pk_mul_f32 v[70:71], v[70:71], v[252:253]
	v_lshlrev_b32_e32 v178, 16, v150
	v_and_b32_e32 v179, 0xffff0000, v150
	v_pk_mul_f32 v[64:65], v[64:65], v[178:179]
	v_lshlrev_b32_e32 v244, 16, v151
	v_and_b32_e32 v245, 0xffff0000, v151
	v_pk_mul_f32 v[66:67], v[66:67], v[244:245]
	v_lshlrev_b32_e32 v246, 16, v156
	v_and_b32_e32 v247, 0xffff0000, v156
	v_pk_add_f32 v[68:69], v[68:69], v[246:247]
	v_lshlrev_b32_e32 v252, 16, v157
	v_and_b32_e32 v253, 0xffff0000, v157
	v_pk_add_f32 v[70:71], v[70:71], v[252:253]
	v_lshlrev_b32_e32 v178, 16, v158
	v_and_b32_e32 v179, 0xffff0000, v158
	v_pk_add_f32 v[64:65], v[64:65], v[178:179]
	v_lshlrev_b32_e32 v244, 16, v159
	v_and_b32_e32 v245, 0xffff0000, v159
	v_pk_add_f32 v[66:67], v[66:67], v[244:245]
	v_cvt_pk_bf16_f32 v148, v68, v69
	v_cvt_pk_bf16_f32 v149, v70, v71
	v_cvt_pk_bf16_f32 v150, v64, v65
	v_cvt_pk_bf16_f32 v151, v66, v67
	s_mov_b32 s58, 0x40000
	v_lshl_add_u64 v[246:247], v[172:173], 0, s[58:59]
	global_store_dwordx4 v[246:247], v[148:151], off offset:256
	s_waitcnt vmcnt(17)
	v_lshlrev_b32_e32 v252, 16, v140
	v_and_b32_e32 v253, 0xffff0000, v140
	v_pk_mul_f32 v[60:61], v[60:61], v[252:253]
	v_lshlrev_b32_e32 v178, 16, v141
	v_and_b32_e32 v179, 0xffff0000, v141
	v_pk_mul_f32 v[62:63], v[62:63], v[178:179]
	v_lshlrev_b32_e32 v244, 16, v142
	v_and_b32_e32 v245, 0xffff0000, v142
	v_pk_mul_f32 v[56:57], v[56:57], v[244:245]
	v_lshlrev_b32_e32 v246, 16, v143
	v_and_b32_e32 v247, 0xffff0000, v143
	v_pk_mul_f32 v[58:59], v[58:59], v[246:247]
	v_lshlrev_b32_e32 v252, 16, v180
	v_and_b32_e32 v253, 0xffff0000, v180
	v_pk_add_f32 v[60:61], v[60:61], v[252:253]
	v_lshlrev_b32_e32 v178, 16, v181
	v_and_b32_e32 v179, 0xffff0000, v181
	v_pk_add_f32 v[62:63], v[62:63], v[178:179]
	v_lshlrev_b32_e32 v244, 16, v182
	v_and_b32_e32 v245, 0xffff0000, v182
	v_pk_add_f32 v[56:57], v[56:57], v[244:245]
	v_lshlrev_b32_e32 v246, 16, v183
	v_and_b32_e32 v247, 0xffff0000, v183
	v_pk_add_f32 v[58:59], v[58:59], v[246:247]
	v_cvt_pk_bf16_f32 v140, v60, v61
	v_cvt_pk_bf16_f32 v141, v62, v63
	v_cvt_pk_bf16_f32 v142, v56, v57
	v_cvt_pk_bf16_f32 v143, v58, v59
	s_mov_b32 s58, 0x48000
	v_lshl_add_u64 v[252:253], v[172:173], 0, s[58:59]
	global_store_dwordx4 v[252:253], v[140:143], off
	s_waitcnt vmcnt(17)
	v_lshlrev_b32_e32 v178, 16, v144
	v_and_b32_e32 v179, 0xffff0000, v144
	v_pk_mul_f32 v[52:53], v[52:53], v[178:179]
	v_lshlrev_b32_e32 v244, 16, v145
	v_and_b32_e32 v245, 0xffff0000, v145
	v_pk_mul_f32 v[54:55], v[54:55], v[244:245]
	v_lshlrev_b32_e32 v246, 16, v146
	v_and_b32_e32 v247, 0xffff0000, v146
	v_pk_mul_f32 v[48:49], v[48:49], v[246:247]
	v_lshlrev_b32_e32 v252, 16, v147
	v_and_b32_e32 v253, 0xffff0000, v147
	v_pk_mul_f32 v[50:51], v[50:51], v[252:253]
	v_lshlrev_b32_e32 v178, 16, v188
	v_and_b32_e32 v179, 0xffff0000, v188
	v_pk_add_f32 v[52:53], v[52:53], v[178:179]
	v_lshlrev_b32_e32 v244, 16, v189
	v_and_b32_e32 v245, 0xffff0000, v189
	v_pk_add_f32 v[54:55], v[54:55], v[244:245]
	v_lshlrev_b32_e32 v246, 16, v190
	v_and_b32_e32 v247, 0xffff0000, v190
	v_pk_add_f32 v[48:49], v[48:49], v[246:247]
	v_lshlrev_b32_e32 v252, 16, v191
	v_and_b32_e32 v253, 0xffff0000, v191
	v_pk_add_f32 v[50:51], v[50:51], v[252:253]
	v_cvt_pk_bf16_f32 v144, v52, v53
	v_cvt_pk_bf16_f32 v145, v54, v55
	v_cvt_pk_bf16_f32 v146, v48, v49
	v_cvt_pk_bf16_f32 v147, v50, v51
	s_mov_b32 s58, 0x48000
	v_lshl_add_u64 v[178:179], v[172:173], 0, s[58:59]
	global_store_dwordx4 v[178:179], v[144:147], off offset:256
	s_waitcnt vmcnt(15)
	v_lshlrev_b32_e32 v244, 16, v128
	v_and_b32_e32 v245, 0xffff0000, v128
	v_pk_mul_f32 v[40:41], v[40:41], v[244:245]
	v_lshlrev_b32_e32 v246, 16, v129
	v_and_b32_e32 v247, 0xffff0000, v129
	v_pk_mul_f32 v[42:43], v[42:43], v[246:247]
	v_lshlrev_b32_e32 v252, 16, v130
	v_and_b32_e32 v253, 0xffff0000, v130
	v_pk_mul_f32 v[36:37], v[36:37], v[252:253]
	v_lshlrev_b32_e32 v178, 16, v131
	v_and_b32_e32 v179, 0xffff0000, v131
	v_pk_mul_f32 v[38:39], v[38:39], v[178:179]
	v_lshlrev_b32_e32 v244, 16, v184
	v_and_b32_e32 v245, 0xffff0000, v184
	v_pk_add_f32 v[40:41], v[40:41], v[244:245]
	v_lshlrev_b32_e32 v246, 16, v185
	v_and_b32_e32 v247, 0xffff0000, v185
	v_pk_add_f32 v[42:43], v[42:43], v[246:247]
	v_lshlrev_b32_e32 v252, 16, v186
	v_and_b32_e32 v253, 0xffff0000, v186
	v_pk_add_f32 v[36:37], v[36:37], v[252:253]
	v_lshlrev_b32_e32 v178, 16, v187
	v_and_b32_e32 v179, 0xffff0000, v187
	v_pk_add_f32 v[38:39], v[38:39], v[178:179]
	v_cvt_pk_bf16_f32 v128, v40, v41
	v_cvt_pk_bf16_f32 v129, v42, v43
	v_cvt_pk_bf16_f32 v130, v36, v37
	v_cvt_pk_bf16_f32 v131, v38, v39
	s_mov_b32 s58, 0x50000
	v_lshl_add_u64 v[244:245], v[172:173], 0, s[58:59]
	global_store_dwordx4 v[244:245], v[128:131], off
	s_waitcnt vmcnt(15)
	v_lshlrev_b32_e32 v246, 16, v132
	v_and_b32_e32 v247, 0xffff0000, v132
	v_pk_mul_f32 v[28:29], v[28:29], v[246:247]
	v_lshlrev_b32_e32 v252, 16, v133
	v_and_b32_e32 v253, 0xffff0000, v133
	v_pk_mul_f32 v[30:31], v[30:31], v[252:253]
	v_lshlrev_b32_e32 v178, 16, v134
	v_and_b32_e32 v179, 0xffff0000, v134
	v_pk_mul_f32 v[20:21], v[20:21], v[178:179]
	v_lshlrev_b32_e32 v244, 16, v135
	v_and_b32_e32 v245, 0xffff0000, v135
	v_pk_mul_f32 v[22:23], v[22:23], v[244:245]
	v_lshlrev_b32_e32 v246, 16, v192
	v_and_b32_e32 v247, 0xffff0000, v192
	v_pk_add_f32 v[28:29], v[28:29], v[246:247]
	v_lshlrev_b32_e32 v252, 16, v193
	v_and_b32_e32 v253, 0xffff0000, v193
	v_pk_add_f32 v[30:31], v[30:31], v[252:253]
	v_lshlrev_b32_e32 v178, 16, v194
	v_and_b32_e32 v179, 0xffff0000, v194
	v_pk_add_f32 v[20:21], v[20:21], v[178:179]
	v_lshlrev_b32_e32 v244, 16, v195
	v_and_b32_e32 v245, 0xffff0000, v195
	v_pk_add_f32 v[22:23], v[22:23], v[244:245]
	v_cvt_pk_bf16_f32 v132, v28, v29
	v_cvt_pk_bf16_f32 v133, v30, v31
	v_cvt_pk_bf16_f32 v134, v20, v21
	v_cvt_pk_bf16_f32 v135, v22, v23
	s_mov_b32 s58, 0x50000
	v_lshl_add_u64 v[246:247], v[172:173], 0, s[58:59]
	global_store_dwordx4 v[246:247], v[132:135], off offset:256
	s_waitcnt vmcnt(11)
	v_lshlrev_b32_e32 v252, 16, v120
	v_and_b32_e32 v253, 0xffff0000, v120
	v_pk_mul_f32 v[12:13], v[12:13], v[252:253]
	v_lshlrev_b32_e32 v178, 16, v121
	v_and_b32_e32 v179, 0xffff0000, v121
	v_pk_mul_f32 v[14:15], v[14:15], v[178:179]
	v_lshlrev_b32_e32 v244, 16, v122
	v_and_b32_e32 v245, 0xffff0000, v122
	v_pk_mul_f32 v[8:9], v[8:9], v[244:245]
	v_lshlrev_b32_e32 v246, 16, v123
	v_and_b32_e32 v247, 0xffff0000, v123
	v_pk_mul_f32 v[10:11], v[10:11], v[246:247]
	v_lshlrev_b32_e32 v252, 16, v196
	v_and_b32_e32 v253, 0xffff0000, v196
	v_pk_add_f32 v[12:13], v[12:13], v[252:253]
	v_lshlrev_b32_e32 v178, 16, v197
	v_and_b32_e32 v179, 0xffff0000, v197
	v_pk_add_f32 v[14:15], v[14:15], v[178:179]
	v_lshlrev_b32_e32 v244, 16, v198
	v_and_b32_e32 v245, 0xffff0000, v198
	v_pk_add_f32 v[8:9], v[8:9], v[244:245]
	v_lshlrev_b32_e32 v246, 16, v199
	v_and_b32_e32 v247, 0xffff0000, v199
	v_pk_add_f32 v[10:11], v[10:11], v[246:247]
	v_cvt_pk_bf16_f32 v120, v12, v13
	v_cvt_pk_bf16_f32 v121, v14, v15
	v_cvt_pk_bf16_f32 v122, v8, v9
	v_cvt_pk_bf16_f32 v123, v10, v11
	s_mov_b32 s58, 0x58000
	v_lshl_add_u64 v[252:253], v[172:173], 0, s[58:59]
	global_store_dwordx4 v[252:253], v[120:123], off
	s_waitcnt vmcnt(11)
	v_lshlrev_b32_e32 v178, 16, v124
	v_and_b32_e32 v179, 0xffff0000, v124
	v_pk_mul_f32 v[4:5], v[4:5], v[178:179]
	v_lshlrev_b32_e32 v244, 16, v125
	v_and_b32_e32 v245, 0xffff0000, v125
	v_pk_mul_f32 v[6:7], v[6:7], v[244:245]
	v_lshlrev_b32_e32 v246, 16, v126
	v_and_b32_e32 v247, 0xffff0000, v126
	v_pk_mul_f32 v[0:1], v[0:1], v[246:247]
	v_lshlrev_b32_e32 v252, 16, v127
	v_and_b32_e32 v253, 0xffff0000, v127
	v_pk_mul_f32 v[2:3], v[2:3], v[252:253]
	v_lshlrev_b32_e32 v178, 16, v204
	v_and_b32_e32 v179, 0xffff0000, v204
	v_pk_add_f32 v[4:5], v[4:5], v[178:179]
	v_lshlrev_b32_e32 v244, 16, v205
	v_and_b32_e32 v245, 0xffff0000, v205
	v_pk_add_f32 v[6:7], v[6:7], v[244:245]
	v_lshlrev_b32_e32 v246, 16, v206
	v_and_b32_e32 v247, 0xffff0000, v206
	v_pk_add_f32 v[0:1], v[0:1], v[246:247]
	v_lshlrev_b32_e32 v252, 16, v207
	v_and_b32_e32 v253, 0xffff0000, v207
	v_pk_add_f32 v[2:3], v[2:3], v[252:253]
	v_cvt_pk_bf16_f32 v124, v4, v5
	v_cvt_pk_bf16_f32 v125, v6, v7
	v_cvt_pk_bf16_f32 v126, v0, v1
	v_cvt_pk_bf16_f32 v127, v2, v3
	s_mov_b32 s58, 0x58000
	v_lshl_add_u64 v[178:179], v[172:173], 0, s[58:59]
	global_store_dwordx4 v[178:179], v[124:127], off offset:256
	s_branch .Lmepi_done
.Lmepi_z3:
	global_load_dwordx4 v[180:183], v[170:171], off nt
	global_load_dwordx4 v[184:187], v[170:171], off offset:256 nt
	global_load_dwordx4 v[188:191], v[172:173], off
	global_load_dwordx4 v[192:195], v[172:173], off offset:256
	s_mov_b32 s58, 0x20000
	v_lshl_add_u64 v[244:245], v[170:171], 0, s[58:59]
	global_load_dwordx4 v[196:199], v[244:245], off nt
	global_load_dwordx4 v[200:203], v[244:245], off offset:256 nt
	s_mov_b32 s58, 0x8000
	v_lshl_add_u64 v[246:247], v[172:173], 0, s[58:59]
	global_load_dwordx4 v[204:207], v[246:247], off
	global_load_dwordx4 v[208:211], v[246:247], off offset:256
	s_mov_b32 s58, 0x40000
	v_lshl_add_u64 v[252:253], v[170:171], 0, s[58:59]
	global_load_dwordx4 v[222:225], v[252:253], off nt
	global_load_dwordx4 v[226:229], v[252:253], off offset:256 nt
	s_mov_b32 s58, 0x10000
	v_lshl_add_u64 v[178:179], v[172:173], 0, s[58:59]
	global_load_dwordx4 v[234:237], v[178:179], off
	global_load_dwordx4 v[238:241], v[178:179], off offset:256
	s_mov_b32 s58, 0x60000
	v_lshl_add_u64 v[244:245], v[170:171], 0, s[58:59]
	global_load_dwordx4 v[16:19], v[244:245], off nt
	global_load_dwordx4 v[24:27], v[244:245], off offset:256 nt
	s_mov_b32 s58, 0x18000
	v_lshl_add_u64 v[246:247], v[172:173], 0, s[58:59]
	global_load_dwordx4 v[32:35], v[246:247], off
	global_load_dwordx4 v[44:47], v[246:247], off offset:256
	s_mov_b32 s58, 0x100000
	v_lshl_add_u64 v[252:253], v[170:171], 0, s[58:59]
	global_load_dwordx4 v[136:139], v[252:253], off nt
	global_load_dwordx4 v[148:151], v[252:253], off offset:256 nt
	s_mov_b32 s58, 0x40000
	v_lshl_add_u64 v[178:179], v[172:173], 0, s[58:59]
	global_load_dwordx4 v[152:155], v[178:179], off
	global_load_dwordx4 v[156:159], v[178:179], off offset:256
	s_waitcnt vmcnt(17)
	v_lshlrev_b32_e32 v244, 16, v180
	v_and_b32_e32 v245, 0xffff0000, v180
	v_pk_mul_f32 v[144:145], v[144:145], v[244:245]
	v_lshlrev_b32_e32 v246, 16, v181
	v_and_b32_e32 v247, 0xffff0000, v181
	v_pk_mul_f32 v[146:147], v[146:147], v[246:247]
	v_lshlrev_b32_e32 v252, 16, v182
	v_and_b32_e32 v253, 0xffff0000, v182
	v_pk_mul_f32 v[140:141], v[140:141], v[252:253]
	v_lshlrev_b32_e32 v178, 16, v183
	v_and_b32_e32 v179, 0xffff0000, v183
	v_pk_mul_f32 v[142:143], v[142:143], v[178:179]
	v_lshlrev_b32_e32 v244, 16, v188
	v_and_b32_e32 v245, 0xffff0000, v188
	v_pk_add_f32 v[144:145], v[144:145], v[244:245]
	v_lshlrev_b32_e32 v246, 16, v189
	v_and_b32_e32 v247, 0xffff0000, v189
	v_pk_add_f32 v[146:147], v[146:147], v[246:247]
	v_lshlrev_b32_e32 v252, 16, v190
	v_and_b32_e32 v253, 0xffff0000, v190
	v_pk_add_f32 v[140:141], v[140:141], v[252:253]
	v_lshlrev_b32_e32 v178, 16, v191
	v_and_b32_e32 v179, 0xffff0000, v191
	v_pk_add_f32 v[142:143], v[142:143], v[178:179]
	v_cvt_pk_bf16_f32 v180, v144, v145
	v_cvt_pk_bf16_f32 v181, v146, v147
	v_cvt_pk_bf16_f32 v182, v140, v141
	v_cvt_pk_bf16_f32 v183, v142, v143
	global_store_dwordx4 v[172:173], v[180:183], off sc1
	s_waitcnt vmcnt(17)
	v_lshlrev_b32_e32 v244, 16, v184
	v_and_b32_e32 v245, 0xffff0000, v184
	v_pk_mul_f32 v[132:133], v[132:133], v[244:245]
	v_lshlrev_b32_e32 v246, 16, v185
	v_and_b32_e32 v247, 0xffff0000, v185
	v_pk_mul_f32 v[134:135], v[134:135], v[246:247]
	v_lshlrev_b32_e32 v252, 16, v186
	v_and_b32_e32 v253, 0xffff0000, v186
	v_pk_mul_f32 v[128:129], v[128:129], v[252:253]
	v_lshlrev_b32_e32 v178, 16, v187
	v_and_b32_e32 v179, 0xffff0000, v187
	v_pk_mul_f32 v[130:131], v[130:131], v[178:179]
	v_lshlrev_b32_e32 v244, 16, v192
	v_and_b32_e32 v245, 0xffff0000, v192
	v_pk_add_f32 v[132:133], v[132:133], v[244:245]
	v_lshlrev_b32_e32 v246, 16, v193
	v_and_b32_e32 v247, 0xffff0000, v193
	v_pk_add_f32 v[134:135], v[134:135], v[246:247]
	v_lshlrev_b32_e32 v252, 16, v194
	v_and_b32_e32 v253, 0xffff0000, v194
	v_pk_add_f32 v[128:129], v[128:129], v[252:253]
	v_lshlrev_b32_e32 v178, 16, v195
	v_and_b32_e32 v179, 0xffff0000, v195
	v_pk_add_f32 v[130:131], v[130:131], v[178:179]
	v_cvt_pk_bf16_f32 v184, v132, v133
	v_cvt_pk_bf16_f32 v185, v134, v135
	v_cvt_pk_bf16_f32 v186, v128, v129
	v_cvt_pk_bf16_f32 v187, v130, v131
	global_store_dwordx4 v[172:173], v[184:187], off offset:256 sc1
	s_mov_b32 s58, 0x120000
	v_lshl_add_u64 v[244:245], v[170:171], 0, s[58:59]
	global_load_dwordx4 v[140:143], v[244:245], off nt
	global_load_dwordx4 v[144:147], v[244:245], off offset:256 nt
	s_mov_b32 s58, 0x48000
	v_lshl_add_u64 v[246:247], v[172:173], 0, s[58:59]
	global_load_dwordx4 v[180:183], v[246:247], off
	global_load_dwordx4 v[188:191], v[246:247], off offset:256
	s_mov_b32 s58, 0x140000
	v_lshl_add_u64 v[252:253], v[170:171], 0, s[58:59]
	global_load_dwordx4 v[128:131], v[252:253], off nt
	global_load_dwordx4 v[132:135], v[252:253], off offset:256 nt
	s_mov_b32 s58, 0x50000
	v_lshl_add_u64 v[178:179], v[172:173], 0, s[58:59]
	global_load_dwordx4 v[184:187], v[178:179], off
	global_load_dwordx4 v[192:195], v[178:179], off offset:256
	s_waitcnt vmcnt(23)
	v_lshlrev_b32_e32 v244, 16, v196
	v_and_b32_e32 v245, 0xffff0000, v196
	v_pk_mul_f32 v[124:125], v[124:125], v[244:245]
	v_lshlrev_b32_e32 v246, 16, v197
	v_and_b32_e32 v247, 0xffff0000, v197
	v_pk_mul_f32 v[126:127], v[126:127], v[246:247]
	v_lshlrev_b32_e32 v252, 16, v198
	v_and_b32_e32 v253, 0xffff0000, v198
	v_pk_mul_f32 v[120:121], v[120:121], v[252:253]
	v_lshlrev_b32_e32 v178, 16, v199
	v_and_b32_e32 v179, 0xffff0000, v199
	v_pk_mul_f32 v[122:123], v[122:123], v[178:179]
	v_lshlrev_b32_e32 v244, 16, v204
	v_and_b32_e32 v245, 0xffff0000, v204
	v_pk_add_f32 v[124:125], v[124:125], v[244:245]
	v_lshlrev_b32_e32 v246, 16, v205
	v_and_b32_e32 v247, 0xffff0000, v205
	v_pk_add_f32 v[126:127], v[126:127], v[246:247]
	v_lshlrev_b32_e32 v252, 16, v206
	v_and_b32_e32 v253, 0xffff0000, v206
	v_pk_add_f32 v[120:121], v[120:121], v[252:253]
	v_lshlrev_b32_e32 v178, 16, v207
	v_and_b32_e32 v179, 0xffff0000, v207
	v_pk_add_f32 v[122:123], v[122:123], v[178:179]
	v_cvt_pk_bf16_f32 v196, v124, v125
	v_cvt_pk_bf16_f32 v197, v126, v127
	v_cvt_pk_bf16_f32 v198, v120, v121
	v_cvt_pk_bf16_f32 v199, v122, v123
	s_mov_b32 s58, 0x8000
	v_lshl_add_u64 v[244:245], v[172:173], 0, s[58:59]
	global_store_dwordx4 v[244:245], v[196:199], off sc1
	s_waitcnt vmcnt(23)
	v_lshlrev_b32_e32 v246, 16, v200
	v_and_b32_e32 v247, 0xffff0000, v200
	v_pk_mul_f32 v[116:117], v[116:117], v[246:247]
	v_lshlrev_b32_e32 v252, 16, v201
	v_and_b32_e32 v253, 0xffff0000, v201
	v_pk_mul_f32 v[118:119], v[118:119], v[252:253]
	v_lshlrev_b32_e32 v178, 16, v202
	v_and_b32_e32 v179, 0xffff0000, v202
	v_pk_mul_f32 v[112:113], v[112:113], v[178:179]
	v_lshlrev_b32_e32 v244, 16, v203
	v_and_b32_e32 v245, 0xffff0000, v203
	v_pk_mul_f32 v[114:115], v[114:115], v[244:245]
	v_lshlrev_b32_e32 v246, 16, v208
	v_and_b32_e32 v247, 0xffff0000, v208
	v_pk_add_f32 v[116:117], v[116:117], v[246:247]
	v_lshlrev_b32_e32 v252, 16, v209
	v_and_b32_e32 v253, 0xffff0000, v209
	v_pk_add_f32 v[118:119], v[118:119], v[252:253]
	v_lshlrev_b32_e32 v178, 16, v210
	v_and_b32_e32 v179, 0xffff0000, v210
	v_pk_add_f32 v[112:113], v[112:113], v[178:179]
	v_lshlrev_b32_e32 v244, 16, v211
	v_and_b32_e32 v245, 0xffff0000, v211
	v_pk_add_f32 v[114:115], v[114:115], v[244:245]
	v_cvt_pk_bf16_f32 v200, v116, v117
	v_cvt_pk_bf16_f32 v201, v118, v119
	v_cvt_pk_bf16_f32 v202, v112, v113
	v_cvt_pk_bf16_f32 v203, v114, v115
	s_mov_b32 s58, 0x8000
	v_lshl_add_u64 v[246:247], v[172:173], 0, s[58:59]
	global_store_dwordx4 v[246:247], v[200:203], off offset:256 sc1
	s_mov_b32 s58, 0x160000
	v_lshl_add_u64 v[252:253], v[170:171], 0, s[58:59]
	global_load_dwordx4 v[120:123], v[252:253], off nt
	global_load_dwordx4 v[124:127], v[252:253], off offset:256 nt
	s_mov_b32 s58, 0x58000
	v_lshl_add_u64 v[178:179], v[172:173], 0, s[58:59]
	global_load_dwordx4 v[196:199], v[178:179], off
	global_load_dwordx4 v[204:207], v[178:179], off offset:256
	s_waitcnt vmcnt(25)
	v_lshlrev_b32_e32 v244, 16, v222
	v_and_b32_e32 v245, 0xffff0000, v222
	v_pk_mul_f32 v[108:109], v[108:109], v[244:245]
	v_lshlrev_b32_e32 v246, 16, v223
	v_and_b32_e32 v247, 0xffff0000, v223
	v_pk_mul_f32 v[110:111], v[110:111], v[246:247]
	v_lshlrev_b32_e32 v252, 16, v224
	v_and_b32_e32 v253, 0xffff0000, v224
	v_pk_mul_f32 v[104:105], v[104:105], v[252:253]
	v_lshlrev_b32_e32 v178, 16, v225
	v_and_b32_e32 v179, 0xffff0000, v225
	v_pk_mul_f32 v[106:107], v[106:107], v[178:179]
	v_lshlrev_b32_e32 v244, 16, v234
	v_and_b32_e32 v245, 0xffff0000, v234
	v_pk_add_f32 v[108:109], v[108:109], v[244:245]
	v_lshlrev_b32_e32 v246, 16, v235
	v_and_b32_e32 v247, 0xffff0000, v235
	v_pk_add_f32 v[110:111], v[110:111], v[246:247]
	v_lshlrev_b32_e32 v252, 16, v236
	v_and_b32_e32 v253, 0xffff0000, v236
	v_pk_add_f32 v[104:105], v[104:105], v[252:253]
	v_lshlrev_b32_e32 v178, 16, v237
	v_and_b32_e32 v179, 0xffff0000, v237
	v_pk_add_f32 v[106:107], v[106:107], v[178:179]
	v_cvt_pk_bf16_f32 v222, v108, v109
	v_cvt_pk_bf16_f32 v223, v110, v111
	v_cvt_pk_bf16_f32 v224, v104, v105
	v_cvt_pk_bf16_f32 v225, v106, v107
	s_mov_b32 s58, 0x10000
	v_lshl_add_u64 v[244:245], v[172:173], 0, s[58:59]
	global_store_dwordx4 v[244:245], v[222:225], off sc1
	s_waitcnt vmcnt(25)
	v_lshlrev_b32_e32 v246, 16, v226
	v_and_b32_e32 v247, 0xffff0000, v226
	v_pk_mul_f32 v[100:101], v[100:101], v[246:247]
	v_lshlrev_b32_e32 v252, 16, v227
	v_and_b32_e32 v253, 0xffff0000, v227
	v_pk_mul_f32 v[102:103], v[102:103], v[252:253]
	v_lshlrev_b32_e32 v178, 16, v228
	v_and_b32_e32 v179, 0xffff0000, v228
	v_pk_mul_f32 v[96:97], v[96:97], v[178:179]
	v_lshlrev_b32_e32 v244, 16, v229
	v_and_b32_e32 v245, 0xffff0000, v229
	v_pk_mul_f32 v[98:99], v[98:99], v[244:245]
	v_lshlrev_b32_e32 v246, 16, v238
	v_and_b32_e32 v247, 0xffff0000, v238
	v_pk_add_f32 v[100:101], v[100:101], v[246:247]
	v_lshlrev_b32_e32 v252, 16, v239
	v_and_b32_e32 v253, 0xffff0000, v239
	v_pk_add_f32 v[102:103], v[102:103], v[252:253]
	v_lshlrev_b32_e32 v178, 16, v240
	v_and_b32_e32 v179, 0xffff0000, v240
	v_pk_add_f32 v[96:97], v[96:97], v[178:179]
	v_lshlrev_b32_e32 v244, 16, v241
	v_and_b32_e32 v245, 0xffff0000, v241
	v_pk_add_f32 v[98:99], v[98:99], v[244:245]
	v_cvt_pk_bf16_f32 v226, v100, v101
	v_cvt_pk_bf16_f32 v227, v102, v103
	v_cvt_pk_bf16_f32 v228, v96, v97
	v_cvt_pk_bf16_f32 v229, v98, v99
	s_mov_b32 s58, 0x10000
	v_lshl_add_u64 v[246:247], v[172:173], 0, s[58:59]
	global_store_dwordx4 v[246:247], v[226:229], off offset:256 sc1
	s_waitcnt vmcnt(23)
	v_lshlrev_b32_e32 v252, 16, v16
	v_and_b32_e32 v253, 0xffff0000, v16
	v_pk_mul_f32 v[92:93], v[92:93], v[252:253]
	v_lshlrev_b32_e32 v178, 16, v17
	v_and_b32_e32 v179, 0xffff0000, v17
	v_pk_mul_f32 v[94:95], v[94:95], v[178:179]
	v_lshlrev_b32_e32 v244, 16, v18
	v_and_b32_e32 v245, 0xffff0000, v18
	v_pk_mul_f32 v[88:89], v[88:89], v[244:245]
	v_lshlrev_b32_e32 v246, 16, v19
	v_and_b32_e32 v247, 0xffff0000, v19
	v_pk_mul_f32 v[90:91], v[90:91], v[246:247]
	v_lshlrev_b32_e32 v252, 16, v32
	v_and_b32_e32 v253, 0xffff0000, v32
	v_pk_add_f32 v[92:93], v[92:93], v[252:253]
	v_lshlrev_b32_e32 v178, 16, v33
	v_and_b32_e32 v179, 0xffff0000, v33
	v_pk_add_f32 v[94:95], v[94:95], v[178:179]
	v_lshlrev_b32_e32 v244, 16, v34
	v_and_b32_e32 v245, 0xffff0000, v34
	v_pk_add_f32 v[88:89], v[88:89], v[244:245]
	v_lshlrev_b32_e32 v246, 16, v35
	v_and_b32_e32 v247, 0xffff0000, v35
	v_pk_add_f32 v[90:91], v[90:91], v[246:247]
	v_cvt_pk_bf16_f32 v16, v92, v93
	v_cvt_pk_bf16_f32 v17, v94, v95
	v_cvt_pk_bf16_f32 v18, v88, v89
	v_cvt_pk_bf16_f32 v19, v90, v91
	s_mov_b32 s58, 0x18000
	v_lshl_add_u64 v[252:253], v[172:173], 0, s[58:59]
	global_store_dwordx4 v[252:253], v[16:19], off sc1
	s_waitcnt vmcnt(23)
	v_lshlrev_b32_e32 v178, 16, v24
	v_and_b32_e32 v179, 0xffff0000, v24
	v_pk_mul_f32 v[84:85], v[84:85], v[178:179]
	v_lshlrev_b32_e32 v244, 16, v25
	v_and_b32_e32 v245, 0xffff0000, v25
	v_pk_mul_f32 v[86:87], v[86:87], v[244:245]
	v_lshlrev_b32_e32 v246, 16, v26
	v_and_b32_e32 v247, 0xffff0000, v26
	v_pk_mul_f32 v[80:81], v[80:81], v[246:247]
	v_lshlrev_b32_e32 v252, 16, v27
	v_and_b32_e32 v253, 0xffff0000, v27
	v_pk_mul_f32 v[82:83], v[82:83], v[252:253]
	v_lshlrev_b32_e32 v178, 16, v44
	v_and_b32_e32 v179, 0xffff0000, v44
	v_pk_add_f32 v[84:85], v[84:85], v[178:179]
	v_lshlrev_b32_e32 v244, 16, v45
	v_and_b32_e32 v245, 0xffff0000, v45
	v_pk_add_f32 v[86:87], v[86:87], v[244:245]
	v_lshlrev_b32_e32 v246, 16, v46
	v_and_b32_e32 v247, 0xffff0000, v46
	v_pk_add_f32 v[80:81], v[80:81], v[246:247]
	v_lshlrev_b32_e32 v252, 16, v47
	v_and_b32_e32 v253, 0xffff0000, v47
	v_pk_add_f32 v[82:83], v[82:83], v[252:253]
	v_cvt_pk_bf16_f32 v24, v84, v85
	v_cvt_pk_bf16_f32 v25, v86, v87
	v_cvt_pk_bf16_f32 v26, v80, v81
	v_cvt_pk_bf16_f32 v27, v82, v83
	s_mov_b32 s58, 0x18000
	v_lshl_add_u64 v[178:179], v[172:173], 0, s[58:59]
	global_store_dwordx4 v[178:179], v[24:27], off offset:256 sc1
	s_waitcnt vmcnt(21)
	v_lshlrev_b32_e32 v244, 16, v136
	v_and_b32_e32 v245, 0xffff0000, v136
	v_pk_mul_f32 v[76:77], v[76:77], v[244:245]
	v_lshlrev_b32_e32 v246, 16, v137
	v_and_b32_e32 v247, 0xffff0000, v137
	v_pk_mul_f32 v[78:79], v[78:79], v[246:247]
	v_lshlrev_b32_e32 v252, 16, v138
	v_and_b32_e32 v253, 0xffff0000, v138
	v_pk_mul_f32 v[72:73], v[72:73], v[252:253]
	v_lshlrev_b32_e32 v178, 16, v139
	v_and_b32_e32 v179, 0xffff0000, v139
	v_pk_mul_f32 v[74:75], v[74:75], v[178:179]
	v_lshlrev_b32_e32 v244, 16, v152
	v_and_b32_e32 v245, 0xffff0000, v152
	v_pk_add_f32 v[76:77], v[76:77], v[244:245]
	v_lshlrev_b32_e32 v246, 16, v153
	v_and_b32_e32 v247, 0xffff0000, v153
	v_pk_add_f32 v[78:79], v[78:79], v[246:247]
	v_lshlrev_b32_e32 v252, 16, v154
	v_and_b32_e32 v253, 0xffff0000, v154
	v_pk_add_f32 v[72:73], v[72:73], v[252:253]
	v_lshlrev_b32_e32 v178, 16, v155
	v_and_b32_e32 v179, 0xffff0000, v155
	v_pk_add_f32 v[74:75], v[74:75], v[178:179]
	v_cvt_pk_bf16_f32 v136, v76, v77
	v_cvt_pk_bf16_f32 v137, v78, v79
	v_cvt_pk_bf16_f32 v138, v72, v73
	v_cvt_pk_bf16_f32 v139, v74, v75
	s_mov_b32 s58, 0x40000
	v_lshl_add_u64 v[244:245], v[172:173], 0, s[58:59]
	global_store_dwordx4 v[244:245], v[136:139], off sc1
	s_waitcnt vmcnt(21)
	v_lshlrev_b32_e32 v246, 16, v148
	v_and_b32_e32 v247, 0xffff0000, v148
	v_pk_mul_f32 v[68:69], v[68:69], v[246:247]
	v_lshlrev_b32_e32 v252, 16, v149
	v_and_b32_e32 v253, 0xffff0000, v149
	v_pk_mul_f32 v[70:71], v[70:71], v[252:253]
	v_lshlrev_b32_e32 v178, 16, v150
	v_and_b32_e32 v179, 0xffff0000, v150
	v_pk_mul_f32 v[64:65], v[64:65], v[178:179]
	v_lshlrev_b32_e32 v244, 16, v151
	v_and_b32_e32 v245, 0xffff0000, v151
	v_pk_mul_f32 v[66:67], v[66:67], v[244:245]
	v_lshlrev_b32_e32 v246, 16, v156
	v_and_b32_e32 v247, 0xffff0000, v156
	v_pk_add_f32 v[68:69], v[68:69], v[246:247]
	v_lshlrev_b32_e32 v252, 16, v157
	v_and_b32_e32 v253, 0xffff0000, v157
	v_pk_add_f32 v[70:71], v[70:71], v[252:253]
	v_lshlrev_b32_e32 v178, 16, v158
	v_and_b32_e32 v179, 0xffff0000, v158
	v_pk_add_f32 v[64:65], v[64:65], v[178:179]
	v_lshlrev_b32_e32 v244, 16, v159
	v_and_b32_e32 v245, 0xffff0000, v159
	v_pk_add_f32 v[66:67], v[66:67], v[244:245]
	v_cvt_pk_bf16_f32 v148, v68, v69
	v_cvt_pk_bf16_f32 v149, v70, v71
	v_cvt_pk_bf16_f32 v150, v64, v65
	v_cvt_pk_bf16_f32 v151, v66, v67
	s_mov_b32 s58, 0x40000
	v_lshl_add_u64 v[246:247], v[172:173], 0, s[58:59]
	global_store_dwordx4 v[246:247], v[148:151], off offset:256 sc1
	s_waitcnt vmcnt(17)
	v_lshlrev_b32_e32 v252, 16, v140
	v_and_b32_e32 v253, 0xffff0000, v140
	v_pk_mul_f32 v[60:61], v[60:61], v[252:253]
	v_lshlrev_b32_e32 v178, 16, v141
	v_and_b32_e32 v179, 0xffff0000, v141
	v_pk_mul_f32 v[62:63], v[62:63], v[178:179]
	v_lshlrev_b32_e32 v244, 16, v142
	v_and_b32_e32 v245, 0xffff0000, v142
	v_pk_mul_f32 v[56:57], v[56:57], v[244:245]
	v_lshlrev_b32_e32 v246, 16, v143
	v_and_b32_e32 v247, 0xffff0000, v143
	v_pk_mul_f32 v[58:59], v[58:59], v[246:247]
	v_lshlrev_b32_e32 v252, 16, v180
	v_and_b32_e32 v253, 0xffff0000, v180
	v_pk_add_f32 v[60:61], v[60:61], v[252:253]
	v_lshlrev_b32_e32 v178, 16, v181
	v_and_b32_e32 v179, 0xffff0000, v181
	v_pk_add_f32 v[62:63], v[62:63], v[178:179]
	v_lshlrev_b32_e32 v244, 16, v182
	v_and_b32_e32 v245, 0xffff0000, v182
	v_pk_add_f32 v[56:57], v[56:57], v[244:245]
	v_lshlrev_b32_e32 v246, 16, v183
	v_and_b32_e32 v247, 0xffff0000, v183
	v_pk_add_f32 v[58:59], v[58:59], v[246:247]
	v_cvt_pk_bf16_f32 v140, v60, v61
	v_cvt_pk_bf16_f32 v141, v62, v63
	v_cvt_pk_bf16_f32 v142, v56, v57
	v_cvt_pk_bf16_f32 v143, v58, v59
	s_mov_b32 s58, 0x48000
	v_lshl_add_u64 v[252:253], v[172:173], 0, s[58:59]
	global_store_dwordx4 v[252:253], v[140:143], off sc1
	s_waitcnt vmcnt(17)
	v_lshlrev_b32_e32 v178, 16, v144
	v_and_b32_e32 v179, 0xffff0000, v144
	v_pk_mul_f32 v[52:53], v[52:53], v[178:179]
	v_lshlrev_b32_e32 v244, 16, v145
	v_and_b32_e32 v245, 0xffff0000, v145
	v_pk_mul_f32 v[54:55], v[54:55], v[244:245]
	v_lshlrev_b32_e32 v246, 16, v146
	v_and_b32_e32 v247, 0xffff0000, v146
	v_pk_mul_f32 v[48:49], v[48:49], v[246:247]
	v_lshlrev_b32_e32 v252, 16, v147
	v_and_b32_e32 v253, 0xffff0000, v147
	v_pk_mul_f32 v[50:51], v[50:51], v[252:253]
	v_lshlrev_b32_e32 v178, 16, v188
	v_and_b32_e32 v179, 0xffff0000, v188
	v_pk_add_f32 v[52:53], v[52:53], v[178:179]
	v_lshlrev_b32_e32 v244, 16, v189
	v_and_b32_e32 v245, 0xffff0000, v189
	v_pk_add_f32 v[54:55], v[54:55], v[244:245]
	v_lshlrev_b32_e32 v246, 16, v190
	v_and_b32_e32 v247, 0xffff0000, v190
	v_pk_add_f32 v[48:49], v[48:49], v[246:247]
	v_lshlrev_b32_e32 v252, 16, v191
	v_and_b32_e32 v253, 0xffff0000, v191
	v_pk_add_f32 v[50:51], v[50:51], v[252:253]
	v_cvt_pk_bf16_f32 v144, v52, v53
	v_cvt_pk_bf16_f32 v145, v54, v55
	v_cvt_pk_bf16_f32 v146, v48, v49
	v_cvt_pk_bf16_f32 v147, v50, v51
	s_mov_b32 s58, 0x48000
	v_lshl_add_u64 v[178:179], v[172:173], 0, s[58:59]
	global_store_dwordx4 v[178:179], v[144:147], off offset:256 sc1
	s_waitcnt vmcnt(15)
	v_lshlrev_b32_e32 v244, 16, v128
	v_and_b32_e32 v245, 0xffff0000, v128
	v_pk_mul_f32 v[40:41], v[40:41], v[244:245]
	v_lshlrev_b32_e32 v246, 16, v129
	v_and_b32_e32 v247, 0xffff0000, v129
	v_pk_mul_f32 v[42:43], v[42:43], v[246:247]
	v_lshlrev_b32_e32 v252, 16, v130
	v_and_b32_e32 v253, 0xffff0000, v130
	v_pk_mul_f32 v[36:37], v[36:37], v[252:253]
	v_lshlrev_b32_e32 v178, 16, v131
	v_and_b32_e32 v179, 0xffff0000, v131
	v_pk_mul_f32 v[38:39], v[38:39], v[178:179]
	v_lshlrev_b32_e32 v244, 16, v184
	v_and_b32_e32 v245, 0xffff0000, v184
	v_pk_add_f32 v[40:41], v[40:41], v[244:245]
	v_lshlrev_b32_e32 v246, 16, v185
	v_and_b32_e32 v247, 0xffff0000, v185
	v_pk_add_f32 v[42:43], v[42:43], v[246:247]
	v_lshlrev_b32_e32 v252, 16, v186
	v_and_b32_e32 v253, 0xffff0000, v186
	v_pk_add_f32 v[36:37], v[36:37], v[252:253]
	v_lshlrev_b32_e32 v178, 16, v187
	v_and_b32_e32 v179, 0xffff0000, v187
	v_pk_add_f32 v[38:39], v[38:39], v[178:179]
	v_cvt_pk_bf16_f32 v128, v40, v41
	v_cvt_pk_bf16_f32 v129, v42, v43
	v_cvt_pk_bf16_f32 v130, v36, v37
	v_cvt_pk_bf16_f32 v131, v38, v39
	s_mov_b32 s58, 0x50000
	v_lshl_add_u64 v[244:245], v[172:173], 0, s[58:59]
	global_store_dwordx4 v[244:245], v[128:131], off sc1
	s_waitcnt vmcnt(15)
	v_lshlrev_b32_e32 v246, 16, v132
	v_and_b32_e32 v247, 0xffff0000, v132
	v_pk_mul_f32 v[28:29], v[28:29], v[246:247]
	v_lshlrev_b32_e32 v252, 16, v133
	v_and_b32_e32 v253, 0xffff0000, v133
	v_pk_mul_f32 v[30:31], v[30:31], v[252:253]
	v_lshlrev_b32_e32 v178, 16, v134
	v_and_b32_e32 v179, 0xffff0000, v134
	v_pk_mul_f32 v[20:21], v[20:21], v[178:179]
	v_lshlrev_b32_e32 v244, 16, v135
	v_and_b32_e32 v245, 0xffff0000, v135
	v_pk_mul_f32 v[22:23], v[22:23], v[244:245]
	v_lshlrev_b32_e32 v246, 16, v192
	v_and_b32_e32 v247, 0xffff0000, v192
	v_pk_add_f32 v[28:29], v[28:29], v[246:247]
	v_lshlrev_b32_e32 v252, 16, v193
	v_and_b32_e32 v253, 0xffff0000, v193
	v_pk_add_f32 v[30:31], v[30:31], v[252:253]
	v_lshlrev_b32_e32 v178, 16, v194
	v_and_b32_e32 v179, 0xffff0000, v194
	v_pk_add_f32 v[20:21], v[20:21], v[178:179]
	v_lshlrev_b32_e32 v244, 16, v195
	v_and_b32_e32 v245, 0xffff0000, v195
	v_pk_add_f32 v[22:23], v[22:23], v[244:245]
	v_cvt_pk_bf16_f32 v132, v28, v29
	v_cvt_pk_bf16_f32 v133, v30, v31
	v_cvt_pk_bf16_f32 v134, v20, v21
	v_cvt_pk_bf16_f32 v135, v22, v23
	s_mov_b32 s58, 0x50000
	v_lshl_add_u64 v[246:247], v[172:173], 0, s[58:59]
	global_store_dwordx4 v[246:247], v[132:135], off offset:256 sc1
	s_waitcnt vmcnt(11)
	v_lshlrev_b32_e32 v252, 16, v120
	v_and_b32_e32 v253, 0xffff0000, v120
	v_pk_mul_f32 v[12:13], v[12:13], v[252:253]
	v_lshlrev_b32_e32 v178, 16, v121
	v_and_b32_e32 v179, 0xffff0000, v121
	v_pk_mul_f32 v[14:15], v[14:15], v[178:179]
	v_lshlrev_b32_e32 v244, 16, v122
	v_and_b32_e32 v245, 0xffff0000, v122
	v_pk_mul_f32 v[8:9], v[8:9], v[244:245]
	v_lshlrev_b32_e32 v246, 16, v123
	v_and_b32_e32 v247, 0xffff0000, v123
	v_pk_mul_f32 v[10:11], v[10:11], v[246:247]
	v_lshlrev_b32_e32 v252, 16, v196
	v_and_b32_e32 v253, 0xffff0000, v196
	v_pk_add_f32 v[12:13], v[12:13], v[252:253]
	v_lshlrev_b32_e32 v178, 16, v197
	v_and_b32_e32 v179, 0xffff0000, v197
	v_pk_add_f32 v[14:15], v[14:15], v[178:179]
	v_lshlrev_b32_e32 v244, 16, v198
	v_and_b32_e32 v245, 0xffff0000, v198
	v_pk_add_f32 v[8:9], v[8:9], v[244:245]
	v_lshlrev_b32_e32 v246, 16, v199
	v_and_b32_e32 v247, 0xffff0000, v199
	v_pk_add_f32 v[10:11], v[10:11], v[246:247]
	v_cvt_pk_bf16_f32 v120, v12, v13
	v_cvt_pk_bf16_f32 v121, v14, v15
	v_cvt_pk_bf16_f32 v122, v8, v9
	v_cvt_pk_bf16_f32 v123, v10, v11
	s_mov_b32 s58, 0x58000
	v_lshl_add_u64 v[252:253], v[172:173], 0, s[58:59]
	global_store_dwordx4 v[252:253], v[120:123], off sc1
	s_waitcnt vmcnt(11)
	v_lshlrev_b32_e32 v178, 16, v124
	v_and_b32_e32 v179, 0xffff0000, v124
	v_pk_mul_f32 v[4:5], v[4:5], v[178:179]
	v_lshlrev_b32_e32 v244, 16, v125
	v_and_b32_e32 v245, 0xffff0000, v125
	v_pk_mul_f32 v[6:7], v[6:7], v[244:245]
	v_lshlrev_b32_e32 v246, 16, v126
	v_and_b32_e32 v247, 0xffff0000, v126
	v_pk_mul_f32 v[0:1], v[0:1], v[246:247]
	v_lshlrev_b32_e32 v252, 16, v127
	v_and_b32_e32 v253, 0xffff0000, v127
	v_pk_mul_f32 v[2:3], v[2:3], v[252:253]
	v_lshlrev_b32_e32 v178, 16, v204
	v_and_b32_e32 v179, 0xffff0000, v204
	v_pk_add_f32 v[4:5], v[4:5], v[178:179]
	v_lshlrev_b32_e32 v244, 16, v205
	v_and_b32_e32 v245, 0xffff0000, v205
	v_pk_add_f32 v[6:7], v[6:7], v[244:245]
	v_lshlrev_b32_e32 v246, 16, v206
	v_and_b32_e32 v247, 0xffff0000, v206
	v_pk_add_f32 v[0:1], v[0:1], v[246:247]
	v_lshlrev_b32_e32 v252, 16, v207
	v_and_b32_e32 v253, 0xffff0000, v207
	v_pk_add_f32 v[2:3], v[2:3], v[252:253]
	v_cvt_pk_bf16_f32 v124, v4, v5
	v_cvt_pk_bf16_f32 v125, v6, v7
	v_cvt_pk_bf16_f32 v126, v0, v1
	v_cvt_pk_bf16_f32 v127, v2, v3
	s_mov_b32 s58, 0x58000
	v_lshl_add_u64 v[178:179], v[172:173], 0, s[58:59]
	global_store_dwordx4 v[178:179], v[124:127], off offset:256 sc1
	s_branch .Lmepi_done
